# MLA variant 4: as variant 3 with the global-load address arithmetic interleaved between the MFMA steps
# speedup vs baseline: 1.0041x; 1.0041x over previous
.LBB0_190:
	s_bitcmp1_b32 s1, 0
	s_cselect_b32 s0, 0x7000, 0
	v_add_u32_e32 v100, s0, v174
	v_add3_u32 v185, s0, v192, v159
	v_add3_u32 v100, v100, v175, v176
	v_add_u32_e32 v184, v100, v177
	v_add_u32_e32 v183, v100, v178
	v_add_u32_e32 v182, v100, v179
	v_add_u32_e32 v181, v100, v180
	ds_read_b64_tr_b16 v[112:113], v184 offset:20480
	ds_read_b64_tr_b16 v[114:115], v184 offset:20992
	ds_read_b64_tr_b16 v[108:109], v183 offset:20480
	ds_read_b64_tr_b16 v[110:111], v183 offset:20992
	ds_read_b64_tr_b16 v[104:105], v182 offset:20480
	ds_read_b64_tr_b16 v[106:107], v182 offset:20992
	ds_read_b64_tr_b16 v[100:101], v181 offset:20480
	ds_read_b64_tr_b16 v[102:103], v181 offset:20992
	ds_read_b128 v[186:189], v185
	ds_read_b128 v[194:197], v185 offset:64
	ds_read_b128 v[202:205], v185 offset:128
	ds_read_b128 v[144:147], v185 offset:1280
	ds_read_b128 v[128:131], v185 offset:1344
	ds_read_b128 v[140:143], v185 offset:1408
	ds_read_b128 v[124:127], v185 offset:10240
	s_waitcnt lgkmcnt(6)
	v_mfma_f32_16x16x32_bf16 v[136:139], v[186:189], v[12:15], v[36:39]
	v_mfma_f32_16x16x32_bf16 v[120:123], v[186:189], v[20:23], v[48:51]
	ds_read_b128 v[186:189], v185 offset:10304
	s_waitcnt lgkmcnt(6)
	v_mfma_f32_16x16x32_bf16 v[136:139], v[194:197], v[16:19], v[136:139]
	v_mfma_f32_16x16x32_bf16 v[120:123], v[194:197], v[24:27], v[120:123]
	ds_read_b128 v[194:197], v185 offset:10368
	s_waitcnt lgkmcnt(6)
	v_mfma_f32_16x16x32_bf16 v[136:139], v[202:205], v[0:3], v[136:139]
	v_mfma_f32_16x16x32_bf16 v[120:123], v[202:205], v[4:7], v[120:123]
	ds_read_b128 v[202:205], v185 offset:11520
	s_andn2_b32 s0, 1, s1
	s_mulk_i32 s0, 0x7000
	s_add_i32 s10, s1, 1
	v_add3_u32 v132, s0, v151, v155
	v_add3_u32 v133, s0, v157, v170
	v_add_u32_e32 v134, s0, v171
	s_waitcnt vmcnt(2)
	ds_write_b128 v132, v[8:11]
	v_add3_u32 v134, v134, v173, v172
	s_add_i32 s0, s1, 3
	s_min_u32 s0, s0, s83
	s_waitcnt vmcnt(0)
	ds_write_b128 v133, v[28:31]
	s_lshl_b32 s0, s0, 6
	ds_write_b128 v134, v[32:35] offset:20480
	s_waitcnt lgkmcnt(9)
	v_mfma_f32_16x16x32_bf16 v[132:135], v[144:147], v[12:15], v[36:39]
	v_add_u32_e32 v8, s0, v154
	v_add_u32_e32 v28, s0, v156
	v_mfma_f32_16x16x32_bf16 v[116:119], v[144:147], v[20:23], v[48:51]
	s_add_i32 s0, s1, 2
	v_ashrrev_i32_e32 v9, 31, v8
	s_waitcnt lgkmcnt(8)
	v_mfma_f32_16x16x32_bf16 v[132:135], v[128:131], v[16:19], v[132:135]
	v_ashrrev_i32_e32 v29, 31, v28
	s_min_u32 s0, s0, s83
	v_mfma_f32_16x16x32_bf16 v[116:119], v[128:131], v[24:27], v[116:119]
	v_lshlrev_b64 v[10:11], 11, v[8:9]
	v_lshlrev_b64 v[8:9], 6, v[8:9]
	s_waitcnt lgkmcnt(7)
	v_mfma_f32_16x16x32_bf16 v[132:135], v[140:143], v[0:3], v[132:135]
	v_lshlrev_b64 v[30:31], 11, v[28:29]
	v_lshlrev_b64 v[28:29], 6, v[28:29]
	v_mfma_f32_16x16x32_bf16 v[116:119], v[140:143], v[4:7], v[116:119]
	v_lshl_add_u32 v32, s0, 6, v158
	v_lshl_add_u64 v[8:9], v[162:163], 0, v[8:9]
	s_waitcnt lgkmcnt(6)
	v_mfma_f32_16x16x32_bf16 v[140:143], v[124:127], v[12:15], v[36:39]
	v_lshl_add_u64 v[28:29], v[166:167], 0, v[28:29]
	v_ashrrev_i32_e32 v33, 31, v32
	v_mfma_f32_16x16x32_bf16 v[124:127], v[124:127], v[20:23], v[48:51]
	v_lshl_add_u64 v[10:11], v[164:165], 0, v[10:11]
	v_lshl_add_u64 v[8:9], v[8:9], 0, s[58:59]
	s_waitcnt lgkmcnt(5)
	v_mfma_f32_16x16x32_bf16 v[140:143], v[186:189], v[16:19], v[140:143]
	v_lshl_add_u64 v[30:31], v[168:169], 0, v[30:31]
	v_lshl_add_u64 v[28:29], v[28:29], 0, s[58:59]
	v_mfma_f32_16x16x32_bf16 v[124:127], v[186:189], v[24:27], v[124:127]
	v_lshlrev_b64 v[32:33], 11, v[32:33]
	v_cndmask_b32_e64 v9, v9, v11, s[6:7]
	ds_read_b128 v[186:189], v185 offset:11584
	s_waitcnt lgkmcnt(5)
	v_mfma_f32_16x16x32_bf16 v[140:143], v[194:197], v[0:3], v[140:143]
	v_cndmask_b32_e64 v8, v8, v10, s[6:7]
	v_cndmask_b32_e64 v29, v29, v31, s[8:9]
	v_mfma_f32_16x16x32_bf16 v[124:127], v[194:197], v[4:7], v[124:127]
	v_cndmask_b32_e64 v28, v28, v30, s[8:9]
	v_lshl_add_u64 v[32:33], v[160:161], 0, v[32:33]
	ds_read_b128 v[194:197], v185 offset:11648
	s_waitcnt lgkmcnt(5)
	v_mfma_f32_16x16x32_bf16 v[144:147], v[202:205], v[12:15], v[36:39]
	global_load_dwordx4 v[8:11], v[8:9], off
	global_load_dwordx4 v[28:31], v[28:29], off
	v_mfma_f32_16x16x32_bf16 v[128:131], v[202:205], v[20:23], v[48:51]
	global_load_dwordx4 v[32:35], v[32:33], off offset:128
	s_waitcnt lgkmcnt(1)
	v_mfma_f32_16x16x32_bf16 v[144:147], v[186:189], v[16:19], v[144:147]
	v_mfma_f32_16x16x32_bf16 v[128:131], v[186:189], v[24:27], v[128:131]
	s_waitcnt lgkmcnt(0)
	v_mfma_f32_16x16x32_bf16 v[144:147], v[194:197], v[0:3], v[144:147]
	v_mfma_f32_16x16x32_bf16 v[128:131], v[194:197], v[4:7], v[128:131]
	s_cmp_ge_u32 s10, s82
	s_cbranch_scc1 .LBB0_196
	s_cmp_lg_u32 s1, 0
	s_cselect_b64 s[0:1], -1, 0
	s_and_b32 s11, s10, 3
	s_cmp_lg_u32 s11, 0
	s_cselect_b64 s[14:15], -1, 0
	s_and_b64 s[0:1], s[0:1], s[14:15]
	s_and_b64 vcc, exec, s[0:1]
	s_cbranch_vccnz .LBB0_196
	v_max_f32_e32 v185, v137, v137
	v_max_f32_e32 v186, v136, v136
	v_max_f32_e32 v185, v186, v185
	v_max3_f32 v185, v185, v138, v139
	v_max3_f32 v185, v185, v132, v133
	v_max3_f32 v185, v185, v134, v135
	v_max3_f32 v185, v185, v140, v141
	v_max3_f32 v185, v185, v142, v143
	v_max3_f32 v185, v185, v144, v145
	v_max3_f32 v185, v185, v146, v147
	v_mov_b32_e32 v186, v185
	s_nop 1
	v_permlane16_swap_b32_e32 v185, v186
	v_max_f32_e32 v186, v186, v186
	v_max_f32_e32 v185, v185, v185
	v_max_f32_e32 v185, v185, v186
	v_mov_b32_e32 v186, v185
	s_nop 1
	v_permlane32_swap_b32_e32 v185, v186
	v_max_f32_e32 v186, v186, v186
	v_max_f32_e32 v185, v185, v185
	v_max_f32_e32 v185, v185, v186
	v_cmp_lt_f32_e32 vcc, s44, v185
	s_cbranch_vccz .LBB0_194
	s_nop 0
	v_cndmask_b32_e32 v185, 0, v185, vcc
	v_exp_f32_e64 v186, -v185
	v_lshlrev_b32_e32 v188, 16, v56
	v_and_b32_e32 v189, 0xffff0000, v56
	v_sub_f32_e32 v139, v139, v185
	v_pk_mul_f32 v[188:189], v[186:187], v[188:189] op_sel_hi:[0,1]
	v_cvt_pk_bf16_f32 v56, v188, v189
	v_lshlrev_b32_e32 v188, 16, v57
	v_and_b32_e32 v189, 0xffff0000, v57
	v_pk_mul_f32 v[188:189], v[186:187], v[188:189] op_sel_hi:[0,1]
	v_cvt_pk_bf16_f32 v57, v188, v189
	v_lshlrev_b32_e32 v188, 16, v58
	v_and_b32_e32 v189, 0xffff0000, v58
	v_pk_mul_f32 v[188:189], v[186:187], v[188:189] op_sel_hi:[0,1]
	v_cvt_pk_bf16_f32 v58, v188, v189
	v_lshlrev_b32_e32 v188, 16, v59
	v_and_b32_e32 v189, 0xffff0000, v59
	v_pk_mul_f32 v[188:189], v[186:187], v[188:189] op_sel_hi:[0,1]
	v_cvt_pk_bf16_f32 v59, v188, v189
	v_lshlrev_b32_e32 v188, 16, v52
	v_and_b32_e32 v189, 0xffff0000, v52
	v_pk_mul_f32 v[188:189], v[186:187], v[188:189] op_sel_hi:[0,1]
	v_cvt_pk_bf16_f32 v52, v188, v189
	v_lshlrev_b32_e32 v188, 16, v53
	v_and_b32_e32 v189, 0xffff0000, v53
	v_pk_mul_f32 v[188:189], v[186:187], v[188:189] op_sel_hi:[0,1]
	v_cvt_pk_bf16_f32 v53, v188, v189
	v_lshlrev_b32_e32 v188, 16, v54
	v_and_b32_e32 v189, 0xffff0000, v54
	v_pk_mul_f32 v[188:189], v[186:187], v[188:189] op_sel_hi:[0,1]
	v_cvt_pk_bf16_f32 v54, v188, v189
	v_lshlrev_b32_e32 v188, 16, v55
	v_and_b32_e32 v189, 0xffff0000, v55
	v_pk_mul_f32 v[78:79], v[78:79], v[186:187] op_sel_hi:[1,0]
	v_pk_mul_f32 v[76:77], v[76:77], v[186:187] op_sel_hi:[1,0]
	v_pk_mul_f32 v[98:99], v[98:99], v[186:187] op_sel_hi:[1,0]
	v_pk_mul_f32 v[96:97], v[96:97], v[186:187] op_sel_hi:[1,0]
	v_pk_mul_f32 v[94:95], v[94:95], v[186:187] op_sel_hi:[1,0]
	v_pk_mul_f32 v[92:93], v[92:93], v[186:187] op_sel_hi:[1,0]
	v_pk_mul_f32 v[86:87], v[86:87], v[186:187] op_sel_hi:[1,0]
	v_pk_mul_f32 v[84:85], v[84:85], v[186:187] op_sel_hi:[1,0]
	v_pk_mul_f32 v[42:43], v[42:43], v[186:187] op_sel_hi:[1,0]
	v_pk_mul_f32 v[40:41], v[40:41], v[186:187] op_sel_hi:[1,0]
	v_pk_mul_f32 v[186:187], v[186:187], v[188:189] op_sel_hi:[0,1]
	v_sub_f32_e32 v138, v138, v185
	v_sub_f32_e32 v137, v137, v185
	v_sub_f32_e32 v136, v136, v185
	v_sub_f32_e32 v135, v135, v185
	v_sub_f32_e32 v134, v134, v185
	v_sub_f32_e32 v133, v133, v185
	v_sub_f32_e32 v132, v132, v185
	v_sub_f32_e32 v143, v143, v185
	v_sub_f32_e32 v142, v142, v185
	v_sub_f32_e32 v141, v141, v185
	v_sub_f32_e32 v140, v140, v185
	v_sub_f32_e32 v147, v147, v185
	v_sub_f32_e32 v146, v146, v185
	v_sub_f32_e32 v145, v145, v185
	v_sub_f32_e32 v144, v144, v185
	v_cvt_pk_bf16_f32 v55, v186, v187
	v_sub_f32_e32 v39, v39, v185
	v_sub_f32_e32 v38, v38, v185
	v_sub_f32_e32 v37, v37, v185
	v_sub_f32_e32 v36, v36, v185
